# v095 + half of the CUs of every XCD enter the P1 GEMM phase ~1 us later so the tile-epilogue store bursts of the two groups do not coincide
# baseline (speedup 1.0000x reference)
; #define PG8_STAGE(bufoff, gbase, voff) do { _Pragma("unroll") for (int _i = 0; _i < 2; ++_i) \
;         __builtin_amdgcn_global_load_lds((const unsigned*)((const char*)(gbase) + (voff)[_i]), (PG8_LAS unsigned*)(lds + (bufoff) + ldsw + _i * 8192), 16, 0, 0); } while (0)
; #define PG8_WAIT_V(n) asm volatile("s_waitcnt vmcnt(" #n ")" ::: "memory")
; #define PG8_BAR __builtin_amdgcn_s_barrier()
; template <class Epi, class Sched, bool ALIGN_EPI = false, bool SP2 = false, bool RS = false, bool BPRE = false>
; __device__ __forceinline__ void gemm_phase(PG8_LAS unsigned char* lds, const Gemm g, const Sched& S, const Epi& E, const float* rs_ss = nullptr, PG8_LAS float* rs_tab = nullptr) {
;     ...
;         PG8_WAIT_V(2); PG8_BAR;
;         PG8_STAGE(PG8_SB(1, 0), cB + kstep, voffB); PG8_STAGE(PG8_SA(1, 0), cA + kstep, voffA); PG8_STAGE(PG8_SB(1, 1), cB + hstep + kstep, voffB);
;         PG8_WAIT_V(6); PG8_BAR;
.LBB0_190:
	s_and_b32 s5, s0, 3
	s_ashr_i32 s77, s3, 31
	s_ashr_i32 s78, s2, 31
	s_lshl_b32 s12, s7, 13
	s_lshl_b32 s13, s5, 12
	s_add_u32 s0, s58, 0x4000
	s_addc_u32 s1, s59, 0
	s_add_i32 m0, s72, 0x18000
	v_lshl_add_u64 v[4:5], s[0:1], 0, v[138:139]
	s_waitcnt vmcnt(2)
	s_barrier
	global_load_lds_dwordx4 v[4:5], off
	s_add_i32 m0, s72, 0x1a000
	v_lshl_add_u64 v[4:5], s[0:1], 0, v[140:141]
	s_add_u32 s0, s56, 0x4000
	s_addc_u32 s1, s57, 0
	s_add_i32 s79, s72, 0x8000
	global_load_lds_dwordx4 v[4:5], off
	v_lshl_add_u64 v[4:5], s[0:1], 0, v[138:139]
	s_mov_b32 m0, s79
	s_add_i32 s80, s72, 0xa000
	global_load_lds_dwordx4 v[4:5], off
	v_lshl_add_u64 v[4:5], s[0:1], 0, v[140:141]
	s_add_u32 s0, s58, 0x84000
	s_mov_b32 m0, s80
	s_addc_u32 s1, s59, 0
	global_load_lds_dwordx4 v[4:5], off
	s_add_i32 m0, s72, 0x1c000
	v_lshl_add_u64 v[4:5], s[0:1], 0, v[138:139]
	global_load_lds_dwordx4 v[4:5], off
	v_lshl_add_u64 v[4:5], s[0:1], 0, v[140:141]
	s_add_i32 m0, s72, 0x1e000
	v_and_b32_e32 v6, 48, v0
	global_load_lds_dwordx4 v[4:5], off
	v_lshlrev_b32_e32 v1, 6, v0
	s_movk_i32 s0, 0x3c0
	v_and_b32_e32 v4, 15, v0
	v_and_or_b32 v7, v1, s0, v6
	v_lshlrev_b32_e32 v1, 2, v0
	v_bfe_u32 v5, v0, 4, 2
	v_and_b32_e32 v8, 32, v1
	v_lshl_or_b32 v1, s7, 6, v4
	v_lshlrev_b32_e32 v4, 6, v4
	v_or_b32_e32 v6, v4, v6
	s_waitcnt vmcnt(6)
	s_cmpk_lt_u32 s6, 0x100
	v_lshl_or_b32 v4, v5, 4, v4
	v_cmp_eq_u32_e64 s[0:1], 0, v5
	v_bitop3_b32 v6, v6, s12, v8 bitop3:0xde
	v_bitop3_b32 v160, s13, v7, v8 bitop3:0xf6
	s_cselect_b64 s[12:13], -1, 0
	s_lshl_b32 s6, s5, 1
	v_lshl_or_b32 v4, s5, 10, v4
	v_mov_b32_e32 v5, v142
	v_add_u32_e32 v146, v2, v3
	s_add_i32 s83, 0, 0x10000
	s_add_i32 s86, 0, 0x14000
	v_mbcnt_lo_u32_b32 v2, -1, 0
	s_or_b32 s81, s6, 0xffffffa0
	v_lshl_add_u64 v[144:145], s[36:37], 0, v[4:5]
	v_mov_b32_e32 v147, v142
	v_mov_b64_e32 v[148:149], 0x700
	v_mov_b64_e32 v[150:151], 0x6ff
	s_movk_i32 s82, 0xe1
	v_add_u32_e32 v161, s83, v160
	v_add_u32_e32 v162, s86, v160
	v_add_u32_e32 v163, 0, v6
	s_mov_b32 s14, 0x3db8aa3b
	v_mbcnt_hi_u32_b32 v164, -1, v2
	s_barrier
	s_bitcmp1_b32 s2, 3
	s_cbranch_scc0 .Lstagger_p1
	s_sleep 40
